# prompt unit tails: gate loads and mix stores coalesced to whole 128-byte rows, redistributed through a wave-private LDS image
# speedup vs baseline: 1.0168x; 1.0081x over previous
; DI unsigned pk2(float a, float b) { f32x2 v = {a, b}; bf16x2v r = __builtin_convertvector(v, bf16x2v); return __builtin_bit_cast(unsigned, r); }
; DI float bflo(unsigned w) { return __uint_as_float(w << 16); }
; DI float bfhi(unsigned w) { return __uint_as_float(w & 0xffff0000u); }
; DI void store_gated(const AttnState& st, const bf16_t* sg, bf16_t* mo, int hh) {
; #pragma unroll
;     for (int dt = 0; dt < 2; ++dt)
; #pragma unroll
;         for (int g = 0; g < 4; ++g) {
;             const int d = 32 * dt + 8 * g + 4 * hh;
;             const u32x2 gv = *(const u32x2*)(sg + d);
;             const f32x16& o = dt == 0 ? st.o0 : st.o1;
;             const float a0 = o[4 * g] * bflo(gv[0]), a1 = o[4 * g + 1] * bfhi(gv[0]), a2 = o[4 * g + 2] * bflo(gv[1]), a3 = o[4 * g + 3] * bfhi(gv[1]);
;             *(u32x2*)(mo + d) = (u32x2){pk2(a0, a1), pk2(a2, a3)};
;         }
; }
; DI void prompt_sb_unit(const Params& p, int b, int h, int qt, char* smem) {
;     ...
;         if (qpos < LP) store_gated(st, p.u + (rowb + qpos) * NU + gcol, p.mix + (rowb + qpos) * DM + h * 64, hh);
.LBB0_432:
	s_or_b64 exec, exec, s[8:9]
	v_cmp_gt_i32_e32 vcc, s88, v98
	s_and_saveexec_b64 s[0:1], vcc
	s_xor_b64 s[0:1], exec, s[0:1]
	s_cbranch_execz .LBB0_418
	v_readfirstlane_b32 s36, v96
	s_mov_b32 s37, 0
	s_mov_b64 exec, -1
	s_lshl_b32 s10, s39, 1
	s_lshl_b64 s[8:9], s[36:37], 13
	s_add_u32 s8, s8, s68
	s_addc_u32 s9, s9, s69
	s_add_u32 s8, s8, s10
	s_addc_u32 s9, s9, 0
	s_add_u32 s8, s8, 0xc00
	s_addc_u32 s9, s9, 0
	s_lshl_b64 s[34:35], s[36:37], 11
	s_add_u32 s34, s34, s70
	s_addc_u32 s35, s35, s71
	s_add_u32 s34, s34, s10
	s_addc_u32 s35, s35, 0
	v_lshrrev_b32_e32 v38, 3, v174
	v_and_b32_e32 v36, 7, v174
	v_lshlrev_b32_e32 v36, 4, v36
	v_lshl_or_b32 v32, v38, 13, v36
	v_lshl_or_b32 v33, v38, 11, v36
	v_mul_u32_u24_e32 v38, 0x90, v38
	v_add_u32_e32 v36, v36, v38
	v_lshrrev_b32_e32 v38, 6, v138
	v_mul_u32_u24_e32 v38, 0x2400, v38
	v_add_u32_e32 v38, 0x100, v38
	v_add_u32_e32 v36, v36, v38
	v_and_b32_e32 v37, 31, v174
	v_mul_u32_u24_e32 v37, 0x90, v37
	v_add_u32_e32 v37, v37, v38
	v_lshrrev_b32_e32 v38, 5, v174
	v_lshl_add_u32 v37, v38, 3, v37
	global_load_dwordx4 v[40:43], v32, s[8:9]
	s_add_u32 s8, s8, 0x10000
	s_addc_u32 s9, s9, 0
	global_load_dwordx4 v[44:47], v32, s[8:9]
	s_add_u32 s8, s8, 0x10000
	s_addc_u32 s9, s9, 0
	global_load_dwordx4 v[48:51], v32, s[8:9]
	s_add_u32 s8, s8, 0x10000
	s_addc_u32 s9, s9, 0
	global_load_dwordx4 v[52:55], v32, s[8:9]
	s_waitcnt vmcnt(0) lgkmcnt(0)
	ds_write_b128 v36, v[40:43]
	ds_write_b128 v36, v[44:47] offset:1152
	ds_write_b128 v36, v[48:51] offset:2304
	ds_write_b128 v36, v[52:55] offset:3456
	s_waitcnt lgkmcnt(0)
	ds_read_b64 v[40:41], v37
	ds_read_b64 v[42:43], v37 offset:16
	ds_read_b64 v[44:45], v37 offset:32
	ds_read_b64 v[46:47], v37 offset:48
	ds_read_b64 v[48:49], v37 offset:64
	ds_read_b64 v[50:51], v37 offset:80
	ds_read_b64 v[52:53], v37 offset:96
	ds_read_b64 v[54:55], v37 offset:112
	s_waitcnt lgkmcnt(7)
	v_lshlrev_b32_e32 v56, 16, v40
	v_and_b32_e32 v57, 0xffff0000, v40
	v_lshlrev_b32_e32 v58, 16, v41
	v_and_b32_e32 v59, 0xffff0000, v41
	v_pk_mul_f32 v[16:17], v[16:17], v[56:57]
	v_pk_mul_f32 v[18:19], v[18:19], v[58:59]
	v_cvt_pk_bf16_f32 v16, v16, v17
	v_cvt_pk_bf16_f32 v17, v18, v19
	s_waitcnt lgkmcnt(6)
	v_lshlrev_b32_e32 v60, 16, v42
	v_and_b32_e32 v61, 0xffff0000, v42
	v_lshlrev_b32_e32 v62, 16, v43
	v_and_b32_e32 v63, 0xffff0000, v43
	v_pk_mul_f32 v[20:21], v[20:21], v[60:61]
	v_pk_mul_f32 v[22:23], v[22:23], v[62:63]
	v_cvt_pk_bf16_f32 v20, v20, v21
	v_cvt_pk_bf16_f32 v21, v22, v23
	s_waitcnt lgkmcnt(5)
	v_lshlrev_b32_e32 v56, 16, v44
	v_and_b32_e32 v57, 0xffff0000, v44
	v_lshlrev_b32_e32 v58, 16, v45
	v_and_b32_e32 v59, 0xffff0000, v45
	v_pk_mul_f32 v[24:25], v[24:25], v[56:57]
	v_pk_mul_f32 v[26:27], v[26:27], v[58:59]
	v_cvt_pk_bf16_f32 v24, v24, v25
	v_cvt_pk_bf16_f32 v25, v26, v27
	s_waitcnt lgkmcnt(4)
	v_lshlrev_b32_e32 v60, 16, v46
	v_and_b32_e32 v61, 0xffff0000, v46
	v_lshlrev_b32_e32 v62, 16, v47
	v_and_b32_e32 v63, 0xffff0000, v47
	v_pk_mul_f32 v[28:29], v[28:29], v[60:61]
	v_pk_mul_f32 v[30:31], v[30:31], v[62:63]
	v_cvt_pk_bf16_f32 v28, v28, v29
	v_cvt_pk_bf16_f32 v29, v30, v31
	s_waitcnt lgkmcnt(3)
	v_lshlrev_b32_e32 v56, 16, v48
	v_and_b32_e32 v57, 0xffff0000, v48
	v_lshlrev_b32_e32 v58, 16, v49
	v_and_b32_e32 v59, 0xffff0000, v49
	v_pk_mul_f32 v[0:1], v[0:1], v[56:57]
	v_pk_mul_f32 v[2:3], v[2:3], v[58:59]
	v_cvt_pk_bf16_f32 v0, v0, v1
	v_cvt_pk_bf16_f32 v1, v2, v3
	s_waitcnt lgkmcnt(2)
	v_lshlrev_b32_e32 v60, 16, v50
	v_and_b32_e32 v61, 0xffff0000, v50
	v_lshlrev_b32_e32 v62, 16, v51
	v_and_b32_e32 v63, 0xffff0000, v51
	v_pk_mul_f32 v[4:5], v[4:5], v[60:61]
	v_pk_mul_f32 v[6:7], v[6:7], v[62:63]
	v_cvt_pk_bf16_f32 v4, v4, v5
	v_cvt_pk_bf16_f32 v5, v6, v7
	s_waitcnt lgkmcnt(1)
	v_lshlrev_b32_e32 v56, 16, v52
	v_and_b32_e32 v57, 0xffff0000, v52
	v_lshlrev_b32_e32 v58, 16, v53
	v_and_b32_e32 v59, 0xffff0000, v53
	v_pk_mul_f32 v[8:9], v[8:9], v[56:57]
	v_pk_mul_f32 v[10:11], v[10:11], v[58:59]
	v_cvt_pk_bf16_f32 v8, v8, v9
	v_cvt_pk_bf16_f32 v9, v10, v11
	s_waitcnt lgkmcnt(0)
	v_lshlrev_b32_e32 v60, 16, v54
	v_and_b32_e32 v61, 0xffff0000, v54
	v_lshlrev_b32_e32 v62, 16, v55
	v_and_b32_e32 v63, 0xffff0000, v55
	v_pk_mul_f32 v[12:13], v[12:13], v[60:61]
	v_pk_mul_f32 v[14:15], v[14:15], v[62:63]
	v_cvt_pk_bf16_f32 v12, v12, v13
	v_cvt_pk_bf16_f32 v13, v14, v15
	ds_write_b64 v37, v[16:17]
	ds_write_b64 v37, v[20:21] offset:16
	ds_write_b64 v37, v[24:25] offset:32
	ds_write_b64 v37, v[28:29] offset:48
	ds_write_b64 v37, v[0:1] offset:64
	ds_write_b64 v37, v[4:5] offset:80
	ds_write_b64 v37, v[8:9] offset:96
	ds_write_b64 v37, v[12:13] offset:112
	s_waitcnt lgkmcnt(0)
	ds_read_b128 v[40:43], v36
	ds_read_b128 v[44:47], v36 offset:1152
	ds_read_b128 v[48:51], v36 offset:2304
	ds_read_b128 v[52:55], v36 offset:3456
	s_waitcnt lgkmcnt(3)
	global_store_dwordx4 v33, v[40:43], s[34:35]
	s_add_u32 s34, s34, 0x4000
	s_addc_u32 s35, s35, 0
	s_waitcnt lgkmcnt(2)
	global_store_dwordx4 v33, v[44:47], s[34:35]
	s_add_u32 s34, s34, 0x4000
	s_addc_u32 s35, s35, 0
	s_waitcnt lgkmcnt(1)
	global_store_dwordx4 v33, v[48:51], s[34:35]
	s_add_u32 s34, s34, 0x4000
	s_addc_u32 s35, s35, 0
	s_waitcnt lgkmcnt(0)
	global_store_dwordx4 v33, v[52:55], s[34:35]
	s_branch .LBB0_418

; DI unsigned pk2(float a, float b) { f32x2 v = {a, b}; bf16x2v r = __builtin_convertvector(v, bf16x2v); return __builtin_bit_cast(unsigned, r); }
; DI float bflo(unsigned w) { return __uint_as_float(w << 16); }
; DI float bfhi(unsigned w) { return __uint_as_float(w & 0xffff0000u); }
; DI void store_gated(const AttnState& st, const bf16_t* sg, bf16_t* mo, int hh) {
; #pragma unroll
;     for (int dt = 0; dt < 2; ++dt)
; #pragma unroll
;         for (int g = 0; g < 4; ++g) {
;             const int d = 32 * dt + 8 * g + 4 * hh;
;             const u32x2 gv = *(const u32x2*)(sg + d);
;             const f32x16& o = dt == 0 ? st.o0 : st.o1;
;             const float a0 = o[4 * g] * bflo(gv[0]), a1 = o[4 * g + 1] * bfhi(gv[0]), a2 = o[4 * g + 2] * bflo(gv[1]), a3 = o[4 * g + 3] * bfhi(gv[1]);
;             *(u32x2*)(mo + d) = (u32x2){pk2(a0, a1), pk2(a2, a3)};
;         }
; }
; template <int MODE>
; DI void prompt_unit(const Params& p, int b, int h, int qt, char* smem) {
;     ...
;     if (MODE == 1) { const float lt = st.l + __shfl_xor(st.l, 32); const float inv = 1.0f / lt; st.o0 = st.o0 * inv; st.o1 = st.o1 * inv; }
;     if (wave_valid && qpos < LP) store_gated(st, p.u + (rowb + qpos) * NU + gcol, p.mix + (rowb + qpos) * DM + (MODE == 0 ? 0 : 512) + h * 64, hh);
.LBB0_548:
	v_and_b32_e32 v33, 64, v174
	v_xor_b32_e32 v32, 32, v174
	v_add_u32_e32 v33, 64, v33
	v_cmp_lt_i32_e32 vcc, v32, v33
	s_nop 1
	v_cndmask_b32_e32 v32, v174, v32, vcc
	v_lshlrev_b32_e32 v32, 2, v32
	ds_bpermute_b32 v32, v32, v107
	v_cmp_gt_i32_e32 vcc, s88, v88
	s_and_b64 s[0:1], s[4:5], vcc
	s_and_saveexec_b64 s[4:5], s[0:1]
	s_xor_b64 s[0:1], exec, s[4:5]
	s_cbranch_execz .LBB0_507
	v_ashrrev_i32_e32 v89, 31, v88
	v_lshl_add_u64 v[34:35], v[88:89], 0, s[8:9]
	s_waitcnt lgkmcnt(0)
	v_add_f32_e32 v40, v107, v32
	v_div_scale_f32 v41, s[4:5], v40, v40, 1.0
	v_rcp_f32_e32 v43, v41
	v_div_scale_f32 v42, vcc, 1.0, v40, 1.0
	v_fma_f32 v44, -v41, v43, 1.0
	v_fmac_f32_e32 v43, v44, v43
	v_mul_f32_e32 v44, v42, v43
	v_fma_f32 v45, -v41, v44, v42
	v_fmac_f32_e32 v44, v45, v43
	v_fma_f32 v41, -v41, v44, v42
	v_div_fmas_f32 v41, v41, v43, v44
	v_div_fixup_f32 v40, v41, v40, 1.0
	v_readfirstlane_b32 s38, v34
	s_mov_b32 s39, 0
	s_mov_b64 exec, -1
	s_lshl_b64 s[46:47], s[38:39], 13
	s_add_u32 s46, s46, s68
	s_addc_u32 s47, s47, s69
	s_add_u32 s46, s46, s6
	s_addc_u32 s47, s47, 0
	s_add_u32 s46, s46, 0x1c00
	s_addc_u32 s47, s47, 0
	s_lshl_b64 s[48:49], s[38:39], 11
	s_add_u32 s48, s48, s70
	s_addc_u32 s49, s49, s71
	s_add_u32 s48, s48, s6
	s_addc_u32 s49, s49, 0
	s_add_u32 s48, s48, 0x400
	s_addc_u32 s49, s49, 0
	v_lshrrev_b32_e32 v33, 3, v174
	v_and_b32_e32 v38, 7, v174
	v_lshlrev_b32_e32 v38, 4, v38
	v_lshl_or_b32 v36, v33, 13, v38
	v_lshl_or_b32 v37, v33, 11, v38
	v_mul_u32_u24_e32 v33, 0x90, v33
	v_add_u32_e32 v38, v38, v33
	v_lshrrev_b32_e32 v33, 6, v138
	v_mul_u32_u24_e32 v33, 0x1200, v33
	v_add_u32_e32 v33, 0x10000, v33
	v_add_u32_e32 v38, v38, v33
	v_and_b32_e32 v39, 31, v174
	v_mul_u32_u24_e32 v39, 0x90, v39
	v_add_u32_e32 v39, v39, v33
	v_lshrrev_b32_e32 v33, 5, v174
	v_lshl_add_u32 v39, v33, 3, v39
	global_load_dwordx4 v[48:51], v36, s[46:47]
	s_add_u32 s46, s46, 0x10000
	s_addc_u32 s47, s47, 0
	global_load_dwordx4 v[52:55], v36, s[46:47]
	s_add_u32 s46, s46, 0x10000
	s_addc_u32 s47, s47, 0
	global_load_dwordx4 v[56:59], v36, s[46:47]
	s_add_u32 s46, s46, 0x10000
	s_addc_u32 s47, s47, 0
	global_load_dwordx4 v[60:63], v36, s[46:47]
	s_waitcnt vmcnt(0) lgkmcnt(0)
	ds_write_b128 v38, v[48:51]
	ds_write_b128 v38, v[52:55] offset:1152
	ds_write_b128 v38, v[56:59] offset:2304
	ds_write_b128 v38, v[60:63] offset:3456
	s_waitcnt lgkmcnt(0)
	ds_read_b64 v[48:49], v39
	ds_read_b64 v[50:51], v39 offset:16
	ds_read_b64 v[52:53], v39 offset:32
	ds_read_b64 v[54:55], v39 offset:48
	ds_read_b64 v[56:57], v39 offset:64
	ds_read_b64 v[58:59], v39 offset:80
	ds_read_b64 v[60:61], v39 offset:96
	ds_read_b64 v[62:63], v39 offset:112
	s_waitcnt lgkmcnt(7)
	v_lshlrev_b32_e32 v64, 16, v48
	v_and_b32_e32 v65, 0xffff0000, v48
	v_lshlrev_b32_e32 v66, 16, v49
	v_and_b32_e32 v67, 0xffff0000, v49
	v_pk_mul_f32 v[16:17], v[16:17], v[40:41] op_sel_hi:[1,0]
	v_pk_mul_f32 v[18:19], v[18:19], v[40:41] op_sel_hi:[1,0]
	v_pk_mul_f32 v[16:17], v[16:17], v[64:65]
	v_pk_mul_f32 v[18:19], v[18:19], v[66:67]
	v_cvt_pk_bf16_f32 v16, v16, v17
	v_cvt_pk_bf16_f32 v17, v18, v19
	s_waitcnt lgkmcnt(6)
	v_lshlrev_b32_e32 v68, 16, v50
	v_and_b32_e32 v69, 0xffff0000, v50
	v_lshlrev_b32_e32 v70, 16, v51
	v_and_b32_e32 v71, 0xffff0000, v51
	v_pk_mul_f32 v[20:21], v[20:21], v[40:41] op_sel_hi:[1,0]
	v_pk_mul_f32 v[22:23], v[22:23], v[40:41] op_sel_hi:[1,0]
	v_pk_mul_f32 v[20:21], v[20:21], v[68:69]
	v_pk_mul_f32 v[22:23], v[22:23], v[70:71]
	v_cvt_pk_bf16_f32 v20, v20, v21
	v_cvt_pk_bf16_f32 v21, v22, v23
	s_waitcnt lgkmcnt(5)
	v_lshlrev_b32_e32 v64, 16, v52
	v_and_b32_e32 v65, 0xffff0000, v52
	v_lshlrev_b32_e32 v66, 16, v53
	v_and_b32_e32 v67, 0xffff0000, v53
	v_pk_mul_f32 v[24:25], v[24:25], v[40:41] op_sel_hi:[1,0]
	v_pk_mul_f32 v[26:27], v[26:27], v[40:41] op_sel_hi:[1,0]
	v_pk_mul_f32 v[24:25], v[24:25], v[64:65]
	v_pk_mul_f32 v[26:27], v[26:27], v[66:67]
	v_cvt_pk_bf16_f32 v24, v24, v25
	v_cvt_pk_bf16_f32 v25, v26, v27
	s_waitcnt lgkmcnt(4)
	v_lshlrev_b32_e32 v68, 16, v54
	v_and_b32_e32 v69, 0xffff0000, v54
	v_lshlrev_b32_e32 v70, 16, v55
	v_and_b32_e32 v71, 0xffff0000, v55
	v_pk_mul_f32 v[28:29], v[28:29], v[40:41] op_sel_hi:[1,0]
	v_pk_mul_f32 v[30:31], v[30:31], v[40:41] op_sel_hi:[1,0]
	v_pk_mul_f32 v[28:29], v[28:29], v[68:69]
	v_pk_mul_f32 v[30:31], v[30:31], v[70:71]
	v_cvt_pk_bf16_f32 v28, v28, v29
	v_cvt_pk_bf16_f32 v29, v30, v31
	s_waitcnt lgkmcnt(3)
	v_lshlrev_b32_e32 v64, 16, v56
	v_and_b32_e32 v65, 0xffff0000, v56
	v_lshlrev_b32_e32 v66, 16, v57
	v_and_b32_e32 v67, 0xffff0000, v57
	v_pk_mul_f32 v[0:1], v[0:1], v[40:41] op_sel_hi:[1,0]
	v_pk_mul_f32 v[2:3], v[2:3], v[40:41] op_sel_hi:[1,0]
	v_pk_mul_f32 v[0:1], v[0:1], v[64:65]
	v_pk_mul_f32 v[2:3], v[2:3], v[66:67]
	v_cvt_pk_bf16_f32 v0, v0, v1
	v_cvt_pk_bf16_f32 v1, v2, v3
	s_waitcnt lgkmcnt(2)
	v_lshlrev_b32_e32 v68, 16, v58
	v_and_b32_e32 v69, 0xffff0000, v58
	v_lshlrev_b32_e32 v70, 16, v59
	v_and_b32_e32 v71, 0xffff0000, v59
	v_pk_mul_f32 v[4:5], v[4:5], v[40:41] op_sel_hi:[1,0]
	v_pk_mul_f32 v[6:7], v[6:7], v[40:41] op_sel_hi:[1,0]
	v_pk_mul_f32 v[4:5], v[4:5], v[68:69]
	v_pk_mul_f32 v[6:7], v[6:7], v[70:71]
	v_cvt_pk_bf16_f32 v4, v4, v5
	v_cvt_pk_bf16_f32 v5, v6, v7
	s_waitcnt lgkmcnt(1)
	v_lshlrev_b32_e32 v64, 16, v60
	v_and_b32_e32 v65, 0xffff0000, v60
	v_lshlrev_b32_e32 v66, 16, v61
	v_and_b32_e32 v67, 0xffff0000, v61
	v_pk_mul_f32 v[8:9], v[8:9], v[40:41] op_sel_hi:[1,0]
	v_pk_mul_f32 v[10:11], v[10:11], v[40:41] op_sel_hi:[1,0]
	v_pk_mul_f32 v[8:9], v[8:9], v[64:65]
	v_pk_mul_f32 v[10:11], v[10:11], v[66:67]
	v_cvt_pk_bf16_f32 v8, v8, v9
	v_cvt_pk_bf16_f32 v9, v10, v11
	s_waitcnt lgkmcnt(0)
	v_lshlrev_b32_e32 v68, 16, v62
	v_and_b32_e32 v69, 0xffff0000, v62
	v_lshlrev_b32_e32 v70, 16, v63
	v_and_b32_e32 v71, 0xffff0000, v63
	v_pk_mul_f32 v[12:13], v[12:13], v[40:41] op_sel_hi:[1,0]
	v_pk_mul_f32 v[14:15], v[14:15], v[40:41] op_sel_hi:[1,0]
	v_pk_mul_f32 v[12:13], v[12:13], v[68:69]
	v_pk_mul_f32 v[14:15], v[14:15], v[70:71]
	v_cvt_pk_bf16_f32 v12, v12, v13
	v_cvt_pk_bf16_f32 v13, v14, v15
	ds_write_b64 v39, v[16:17]
	ds_write_b64 v39, v[20:21] offset:16
	ds_write_b64 v39, v[24:25] offset:32
	ds_write_b64 v39, v[28:29] offset:48
	ds_write_b64 v39, v[0:1] offset:64
	ds_write_b64 v39, v[4:5] offset:80
	ds_write_b64 v39, v[8:9] offset:96
	ds_write_b64 v39, v[12:13] offset:112
	s_waitcnt lgkmcnt(0)
	ds_read_b128 v[48:51], v38
	ds_read_b128 v[52:55], v38 offset:1152
	ds_read_b128 v[56:59], v38 offset:2304
	ds_read_b128 v[60:63], v38 offset:3456
	s_waitcnt lgkmcnt(3)
	global_store_dwordx4 v37, v[48:51], s[48:49]
	s_add_u32 s48, s48, 0x4000
	s_addc_u32 s49, s49, 0
	s_waitcnt lgkmcnt(2)
	global_store_dwordx4 v37, v[52:55], s[48:49]
	s_add_u32 s48, s48, 0x4000
	s_addc_u32 s49, s49, 0
	s_waitcnt lgkmcnt(1)
	global_store_dwordx4 v37, v[56:59], s[48:49]
	s_add_u32 s48, s48, 0x4000
	s_addc_u32 s49, s49, 0
	s_waitcnt lgkmcnt(0)
	global_store_dwordx4 v37, v[60:63], s[48:49]
	s_branch .LBB0_507
